# LN2 forget-gate logits: kv_w[:, 2048:2064] slab staged once per workgroup in LDS ([k][quarter][lane]) and read with ds_read_b128 instead of 64-line-per-instruction global loads per row; same f32 arith
# speedup vs baseline: 1.0583x; 1.0519x over previous
.LBB0_1106:
	v_readlane_b32 s34, v254, 0
	v_readlane_b32 s4, v254, 32
	v_readlane_b32 s35, v254, 1
	v_mov_b32_e32 v0, v192
	v_readlane_b32 s5, v254, 33
	s_waitcnt lgkmcnt(0)
	s_load_dwordx8 s[8:15], s[34:35], 0xa8
	s_mov_b32 s16, s20
	s_cmp_lg_u32 s20, 1
	s_cbranch_scc1 .Lln2_nostage
	s_load_dwordx2 s[100:101], s[34:35], 0x58
	v_and_b32_e32 v204, 63, v192
	v_lshlrev_b32_e32 v205, 4, v204
	v_mul_u32_u24_e32 v204, 0x8100, v204
	v_add_u32_e32 v204, 0x2000, v204
	v_readfirstlane_b32 s23, v192
	s_lshr_b32 s23, s23, 6
	s_lshl_b32 s23, s23, 1
	s_add_i32 s24, s23, 0
	s_lshr_b32 s21, s24, 2
	s_mul_i32 s21, s21, 0x204000
	s_and_b32 s22, s24, 3
	s_mul_i32 s22, s22, 0x2040
	s_add_i32 s21, s21, s22
	v_add_u32_e32 v206, s21, v204
	s_lshl_b32 s21, s24, 12
	v_add_u32_e32 v208, s21, v205
	s_add_i32 s24, s23, 1
	s_lshr_b32 s21, s24, 2
	s_mul_i32 s21, s21, 0x204000
	s_and_b32 s22, s24, 3
	s_mul_i32 s22, s22, 0x2040
	s_add_i32 s21, s21, s22
	v_add_u32_e32 v207, s21, v204
	s_lshl_b32 s21, s24, 12
	v_add_u32_e32 v209, s21, v205
	s_waitcnt lgkmcnt(0)
	global_load_dwordx4 v[212:215], v206, s[100:101]
	global_load_dwordx4 v[216:219], v206, s[100:101] offset:16
	global_load_dwordx4 v[220:223], v206, s[100:101] offset:32
	global_load_dwordx4 v[224:227], v206, s[100:101] offset:48
	global_load_dwordx4 v[228:231], v207, s[100:101]
	global_load_dwordx4 v[232:235], v207, s[100:101] offset:16
	global_load_dwordx4 v[236:239], v207, s[100:101] offset:32
	global_load_dwordx4 v[240:243], v207, s[100:101] offset:48
	s_waitcnt vmcnt(0)
	ds_write_b128 v208, v[212:215]
	ds_write_b128 v208, v[216:219] offset:1024
	ds_write_b128 v208, v[220:223] offset:2048
	ds_write_b128 v208, v[224:227] offset:3072
	ds_write_b128 v209, v[228:231]
	ds_write_b128 v209, v[232:235] offset:1024
	ds_write_b128 v209, v[236:239] offset:2048
	ds_write_b128 v209, v[240:243] offset:3072
	s_waitcnt lgkmcnt(0)
	s_barrier
.Lln2_nostage:
	v_and_b32_e32 v2, 63, v0
	s_nop 0
	global_load_ushort v1, v173, s[4:5]
	s_waitcnt lgkmcnt(0)
	s_add_u32 s6, s12, 0x8000
	s_addc_u32 s7, s13, 0
	s_add_u32 s20, s14, 0x4e09000
	s_addc_u32 s21, s15, 0
	s_add_u32 s0, s14, 0x11139000
	s_addc_u32 s4, s15, 0
	s_add_u32 s22, s14, 0x151f9000
	s_addc_u32 s23, s15, 0
	s_add_u32 s24, s14, 0xf0b1000
	v_ashrrev_i32_e32 v0, 6, v0
	s_addc_u32 s25, s15, 0
	v_mul_lo_u32 v3, v0, s42
	s_cmp_lg_u32 s16, 3
	v_add_u32_e32 v0, s2, v3
	s_cselect_b64 s[26:27], -1, 0
	s_cmp_eq_u32 s16, 3
	v_cmp_gt_i32_e32 vcc, s58, v0
	s_cselect_b32 s29, s4, s7
	s_cselect_b32 s28, s0, s6
	s_waitcnt vmcnt(0)
	v_readfirstlane_b32 s0, v1
	v_ashrrev_i32_e32 v1, 31, v0
	s_and_saveexec_b64 s[16:17], vcc
	s_cbranch_execz .LBB0_1108
	v_lshlrev_b64 v[26:27], 11, v[0:1]
	v_lshl_or_b32 v26, v2, 3, v26
	s_mov_b32 s18, 0xfe000000
	v_lshl_add_u64 v[6:7], s[22:23], 0, v[26:27]
	s_mov_b32 s19, -1
	v_lshl_add_u64 v[4:5], s[24:25], 0, v[26:27]
	v_lshl_add_u64 v[6:7], v[6:7], 0, s[18:19]
	v_cmp_gt_i32_e64 s[4:5], s73, v0
	v_lshl_add_u64 v[14:15], s[28:29], 0, v[26:27]
	v_lshl_add_u64 v[18:19], s[20:21], 0, v[26:27]
	v_cndmask_b32_e64 v5, v7, v5, s[4:5]
	v_cndmask_b32_e64 v4, v6, v4, s[4:5]
	v_or_b32_e32 v6, 0x200, v26
	v_mov_b32_e32 v7, v27
	v_lshl_add_u64 v[20:21], s[20:21], 0, v[6:7]
	v_lshl_add_u64 v[8:9], s[24:25], 0, v[6:7]
	v_lshl_add_u64 v[6:7], s[22:23], 0, v[6:7]
	v_lshl_add_u64 v[6:7], v[6:7], 0, s[18:19]
	v_cndmask_b32_e64 v7, v7, v9, s[4:5]
	v_cndmask_b32_e64 v6, v6, v8, s[4:5]
	v_or_b32_e32 v8, 0x400, v26
	v_mov_b32_e32 v9, v27
	v_lshl_add_u64 v[22:23], s[20:21], 0, v[8:9]
	v_lshl_add_u64 v[10:11], s[24:25], 0, v[8:9]
	v_lshl_add_u64 v[8:9], s[22:23], 0, v[8:9]
	v_lshl_add_u64 v[8:9], v[8:9], 0, s[18:19]
	v_cndmask_b32_e64 v9, v9, v11, s[4:5]
	v_cndmask_b32_e64 v8, v8, v10, s[4:5]
	v_or_b32_e32 v26, 0x600, v26
	global_load_dwordx2 v[4:5], v[4:5], off
	v_lshl_add_u64 v[24:25], s[20:21], 0, v[26:27]
	global_load_dwordx2 v[6:7], v[6:7], off
	s_nop 0
	global_load_dwordx2 v[16:17], v[8:9], off
	s_nop 0
	global_load_dwordx2 v[8:9], v[14:15], off
	global_load_dwordx2 v[10:11], v[14:15], off offset:512
	global_load_dwordx2 v[12:13], v[14:15], off offset:1024
	s_nop 0
	global_load_dwordx2 v[14:15], v[14:15], off offset:1536
	v_lshl_add_u64 v[28:29], s[24:25], 0, v[26:27]
	v_lshl_add_u64 v[26:27], s[22:23], 0, v[26:27]
	global_load_dwordx2 v[18:19], v[18:19], off
	s_nop 0
	global_load_dwordx2 v[20:21], v[20:21], off
	s_nop 0
	global_load_dwordx2 v[22:23], v[22:23], off
	s_nop 0
	global_load_dwordx2 v[24:25], v[24:25], off
	v_lshl_add_u64 v[26:27], v[26:27], 0, s[18:19]
	v_cndmask_b32_e64 v27, v27, v29, s[4:5]
	v_cndmask_b32_e64 v26, v26, v28, s[4:5]
	global_load_dwordx2 v[26:27], v[26:27], off

.LBB0_1143:
	s_waitcnt vmcnt(0)
	v_mov_b32_e32 v0, 0
	v_mov_b32_e32 v1, v0
	v_mov_b32_e32 v80, v0
	v_mov_b32_e32 v81, v0
	v_mov_b32_e32 v74, v0
	v_mov_b32_e32 v75, v0
	v_mov_b32_e32 v72, v0
	v_mov_b32_e32 v73, v0
	v_mov_b32_e32 v70, v0
	v_mov_b32_e32 v71, v0
	v_mov_b32_e32 v68, v0
	v_mov_b32_e32 v69, v0
	v_mov_b32_e32 v66, v0
	v_mov_b32_e32 v67, v0
	v_mov_b32_e32 v2, v0
	v_mov_b32_e32 v3, v0
	v_and_b32_e32 v130, 63, v192
	v_lshlrev_b32_e32 v130, 4, v130
	global_load_dwordx2 v[114:115], v[58:59], off offset:-4
	global_load_dwordx2 v[116:117], v[56:57], off offset:-4
	global_load_dwordx2 v[118:119], v[58:59], off offset:508
	global_load_dwordx2 v[120:121], v[56:57], off offset:508
	global_load_dwordx2 v[122:123], v[58:59], off offset:1020
	global_load_dwordx2 v[124:125], v[56:57], off offset:1020
	global_load_dwordx2 v[126:127], v[58:59], off offset:1532
	global_load_dwordx2 v[128:129], v[56:57], off offset:1532
	ds_read_b128 v[204:207], v130 offset:0
	ds_read_b128 v[208:211], v130 offset:1024
	ds_read_b128 v[212:215], v130 offset:2048
	ds_read_b128 v[216:219], v130 offset:3072
	ds_read_b128 v[220:223], v130 offset:4096
	ds_read_b128 v[224:227], v130 offset:5120
	ds_read_b128 v[228:231], v130 offset:6144
	ds_read_b128 v[232:235], v130 offset:7168
	ds_read_b128 v[236:239], v130 offset:8192
	ds_read_b128 v[240:243], v130 offset:9216
	ds_read_b128 v[244:247], v130 offset:10240
	ds_read_b128 v[248:251], v130 offset:11264
	s_waitcnt lgkmcnt(8)
	s_waitcnt vmcnt(6)
	v_lshlrev_b32_e32 v180, 16, v114
	v_lshlrev_b32_e32 v181, 16, v116
	v_add_f32_e32 v174, v180, v181
	v_pk_fma_f32 v[80:81], v[204:205], v[174:175], v[80:81] op_sel_hi:[1,0,1]
	v_pk_fma_f32 v[74:75], v[206:207], v[174:175], v[74:75] op_sel_hi:[1,0,1]
	v_pk_fma_f32 v[72:73], v[208:209], v[174:175], v[72:73] op_sel_hi:[1,0,1]
	v_pk_fma_f32 v[70:71], v[210:211], v[174:175], v[70:71] op_sel_hi:[1,0,1]
	v_pk_fma_f32 v[68:69], v[212:213], v[174:175], v[68:69] op_sel_hi:[1,0,1]
	v_pk_fma_f32 v[66:67], v[214:215], v[174:175], v[66:67] op_sel_hi:[1,0,1]
	v_pk_fma_f32 v[2:3], v[216:217], v[174:175], v[2:3] op_sel_hi:[1,0,1]
	v_pk_fma_f32 v[0:1], v[218:219], v[174:175], v[0:1] op_sel_hi:[1,0,1]
	ds_read_b128 v[204:207], v130 offset:12288
	ds_read_b128 v[208:211], v130 offset:13312
	ds_read_b128 v[212:215], v130 offset:14336
	ds_read_b128 v[216:219], v130 offset:15360
	s_waitcnt lgkmcnt(8)
	v_and_b32_e32 v180, 0xffff0000, v114
	v_and_b32_e32 v181, 0xffff0000, v116
	v_add_f32_e32 v174, v180, v181
	v_pk_fma_f32 v[80:81], v[220:221], v[174:175], v[80:81] op_sel_hi:[1,0,1]
	v_pk_fma_f32 v[74:75], v[222:223], v[174:175], v[74:75] op_sel_hi:[1,0,1]
	v_pk_fma_f32 v[72:73], v[224:225], v[174:175], v[72:73] op_sel_hi:[1,0,1]
	v_pk_fma_f32 v[70:71], v[226:227], v[174:175], v[70:71] op_sel_hi:[1,0,1]
	v_pk_fma_f32 v[68:69], v[228:229], v[174:175], v[68:69] op_sel_hi:[1,0,1]
	v_pk_fma_f32 v[66:67], v[230:231], v[174:175], v[66:67] op_sel_hi:[1,0,1]
	v_pk_fma_f32 v[2:3], v[232:233], v[174:175], v[2:3] op_sel_hi:[1,0,1]
	v_pk_fma_f32 v[0:1], v[234:235], v[174:175], v[0:1] op_sel_hi:[1,0,1]
	ds_read_b128 v[220:223], v130 offset:16384
	ds_read_b128 v[224:227], v130 offset:17408
	ds_read_b128 v[228:231], v130 offset:18432
	ds_read_b128 v[232:235], v130 offset:19456
	s_waitcnt lgkmcnt(8)
	v_lshlrev_b32_e32 v180, 16, v115
	v_lshlrev_b32_e32 v181, 16, v117
	v_add_f32_e32 v174, v180, v181
	v_pk_fma_f32 v[80:81], v[236:237], v[174:175], v[80:81] op_sel_hi:[1,0,1]
	v_pk_fma_f32 v[74:75], v[238:239], v[174:175], v[74:75] op_sel_hi:[1,0,1]
	v_pk_fma_f32 v[72:73], v[240:241], v[174:175], v[72:73] op_sel_hi:[1,0,1]
	v_pk_fma_f32 v[70:71], v[242:243], v[174:175], v[70:71] op_sel_hi:[1,0,1]
	v_pk_fma_f32 v[68:69], v[244:245], v[174:175], v[68:69] op_sel_hi:[1,0,1]
	v_pk_fma_f32 v[66:67], v[246:247], v[174:175], v[66:67] op_sel_hi:[1,0,1]
	v_pk_fma_f32 v[2:3], v[248:249], v[174:175], v[2:3] op_sel_hi:[1,0,1]
	v_pk_fma_f32 v[0:1], v[250:251], v[174:175], v[0:1] op_sel_hi:[1,0,1]
	ds_read_b128 v[236:239], v130 offset:20480
	ds_read_b128 v[240:243], v130 offset:21504
	ds_read_b128 v[244:247], v130 offset:22528
	ds_read_b128 v[248:251], v130 offset:23552
	s_waitcnt lgkmcnt(8)
	v_and_b32_e32 v180, 0xffff0000, v115
	v_and_b32_e32 v181, 0xffff0000, v117
	v_add_f32_e32 v174, v180, v181
	v_pk_fma_f32 v[80:81], v[204:205], v[174:175], v[80:81] op_sel_hi:[1,0,1]
	v_pk_fma_f32 v[74:75], v[206:207], v[174:175], v[74:75] op_sel_hi:[1,0,1]
	v_pk_fma_f32 v[72:73], v[208:209], v[174:175], v[72:73] op_sel_hi:[1,0,1]
	v_pk_fma_f32 v[70:71], v[210:211], v[174:175], v[70:71] op_sel_hi:[1,0,1]
	v_pk_fma_f32 v[68:69], v[212:213], v[174:175], v[68:69] op_sel_hi:[1,0,1]
	v_pk_fma_f32 v[66:67], v[214:215], v[174:175], v[66:67] op_sel_hi:[1,0,1]
	v_pk_fma_f32 v[2:3], v[216:217], v[174:175], v[2:3] op_sel_hi:[1,0,1]
	v_pk_fma_f32 v[0:1], v[218:219], v[174:175], v[0:1] op_sel_hi:[1,0,1]
	ds_read_b128 v[204:207], v130 offset:24576
	ds_read_b128 v[208:211], v130 offset:25600
	ds_read_b128 v[212:215], v130 offset:26624
	ds_read_b128 v[216:219], v130 offset:27648
	s_waitcnt lgkmcnt(8)
	s_waitcnt vmcnt(4)
	v_lshlrev_b32_e32 v180, 16, v118
	v_lshlrev_b32_e32 v181, 16, v120
	v_add_f32_e32 v174, v180, v181
	v_pk_fma_f32 v[80:81], v[220:221], v[174:175], v[80:81] op_sel_hi:[1,0,1]
	v_pk_fma_f32 v[74:75], v[222:223], v[174:175], v[74:75] op_sel_hi:[1,0,1]
	v_pk_fma_f32 v[72:73], v[224:225], v[174:175], v[72:73] op_sel_hi:[1,0,1]
	v_pk_fma_f32 v[70:71], v[226:227], v[174:175], v[70:71] op_sel_hi:[1,0,1]
	v_pk_fma_f32 v[68:69], v[228:229], v[174:175], v[68:69] op_sel_hi:[1,0,1]
	v_pk_fma_f32 v[66:67], v[230:231], v[174:175], v[66:67] op_sel_hi:[1,0,1]
	v_pk_fma_f32 v[2:3], v[232:233], v[174:175], v[2:3] op_sel_hi:[1,0,1]
	v_pk_fma_f32 v[0:1], v[234:235], v[174:175], v[0:1] op_sel_hi:[1,0,1]
	ds_read_b128 v[220:223], v130 offset:28672
	ds_read_b128 v[224:227], v130 offset:29696
	ds_read_b128 v[228:231], v130 offset:30720
	ds_read_b128 v[232:235], v130 offset:31744
	s_waitcnt lgkmcnt(8)
	v_and_b32_e32 v180, 0xffff0000, v118
	v_and_b32_e32 v181, 0xffff0000, v120
	v_add_f32_e32 v174, v180, v181
	v_pk_fma_f32 v[80:81], v[236:237], v[174:175], v[80:81] op_sel_hi:[1,0,1]
	v_pk_fma_f32 v[74:75], v[238:239], v[174:175], v[74:75] op_sel_hi:[1,0,1]
	v_pk_fma_f32 v[72:73], v[240:241], v[174:175], v[72:73] op_sel_hi:[1,0,1]
	v_pk_fma_f32 v[70:71], v[242:243], v[174:175], v[70:71] op_sel_hi:[1,0,1]
	v_pk_fma_f32 v[68:69], v[244:245], v[174:175], v[68:69] op_sel_hi:[1,0,1]
	v_pk_fma_f32 v[66:67], v[246:247], v[174:175], v[66:67] op_sel_hi:[1,0,1]
	v_pk_fma_f32 v[2:3], v[248:249], v[174:175], v[2:3] op_sel_hi:[1,0,1]
	v_pk_fma_f32 v[0:1], v[250:251], v[174:175], v[0:1] op_sel_hi:[1,0,1]
	ds_read_b128 v[236:239], v130 offset:32768
	ds_read_b128 v[240:243], v130 offset:33792
	ds_read_b128 v[244:247], v130 offset:34816
	ds_read_b128 v[248:251], v130 offset:35840
	s_waitcnt lgkmcnt(8)
	v_lshlrev_b32_e32 v180, 16, v119
	v_lshlrev_b32_e32 v181, 16, v121
	v_add_f32_e32 v174, v180, v181
	v_pk_fma_f32 v[80:81], v[204:205], v[174:175], v[80:81] op_sel_hi:[1,0,1]
	v_pk_fma_f32 v[74:75], v[206:207], v[174:175], v[74:75] op_sel_hi:[1,0,1]
	v_pk_fma_f32 v[72:73], v[208:209], v[174:175], v[72:73] op_sel_hi:[1,0,1]
	v_pk_fma_f32 v[70:71], v[210:211], v[174:175], v[70:71] op_sel_hi:[1,0,1]
	v_pk_fma_f32 v[68:69], v[212:213], v[174:175], v[68:69] op_sel_hi:[1,0,1]
	v_pk_fma_f32 v[66:67], v[214:215], v[174:175], v[66:67] op_sel_hi:[1,0,1]
	v_pk_fma_f32 v[2:3], v[216:217], v[174:175], v[2:3] op_sel_hi:[1,0,1]
	v_pk_fma_f32 v[0:1], v[218:219], v[174:175], v[0:1] op_sel_hi:[1,0,1]
	ds_read_b128 v[204:207], v130 offset:36864
	ds_read_b128 v[208:211], v130 offset:37888
	ds_read_b128 v[212:215], v130 offset:38912
	ds_read_b128 v[216:219], v130 offset:39936
	s_waitcnt lgkmcnt(8)
	v_and_b32_e32 v180, 0xffff0000, v119
	v_and_b32_e32 v181, 0xffff0000, v121
	v_add_f32_e32 v174, v180, v181
	v_pk_fma_f32 v[80:81], v[220:221], v[174:175], v[80:81] op_sel_hi:[1,0,1]
	v_pk_fma_f32 v[74:75], v[222:223], v[174:175], v[74:75] op_sel_hi:[1,0,1]
	v_pk_fma_f32 v[72:73], v[224:225], v[174:175], v[72:73] op_sel_hi:[1,0,1]
	v_pk_fma_f32 v[70:71], v[226:227], v[174:175], v[70:71] op_sel_hi:[1,0,1]
	v_pk_fma_f32 v[68:69], v[228:229], v[174:175], v[68:69] op_sel_hi:[1,0,1]
	v_pk_fma_f32 v[66:67], v[230:231], v[174:175], v[66:67] op_sel_hi:[1,0,1]
	v_pk_fma_f32 v[2:3], v[232:233], v[174:175], v[2:3] op_sel_hi:[1,0,1]
	v_pk_fma_f32 v[0:1], v[234:235], v[174:175], v[0:1] op_sel_hi:[1,0,1]
	ds_read_b128 v[220:223], v130 offset:40960
	ds_read_b128 v[224:227], v130 offset:41984
	ds_read_b128 v[228:231], v130 offset:43008
	ds_read_b128 v[232:235], v130 offset:44032
	s_waitcnt lgkmcnt(8)
	s_waitcnt vmcnt(2)
	v_lshlrev_b32_e32 v180, 16, v122
	v_lshlrev_b32_e32 v181, 16, v124
	v_add_f32_e32 v174, v180, v181
	v_pk_fma_f32 v[80:81], v[236:237], v[174:175], v[80:81] op_sel_hi:[1,0,1]
	v_pk_fma_f32 v[74:75], v[238:239], v[174:175], v[74:75] op_sel_hi:[1,0,1]
	v_pk_fma_f32 v[72:73], v[240:241], v[174:175], v[72:73] op_sel_hi:[1,0,1]
	v_pk_fma_f32 v[70:71], v[242:243], v[174:175], v[70:71] op_sel_hi:[1,0,1]
	v_pk_fma_f32 v[68:69], v[244:245], v[174:175], v[68:69] op_sel_hi:[1,0,1]
	v_pk_fma_f32 v[66:67], v[246:247], v[174:175], v[66:67] op_sel_hi:[1,0,1]
	v_pk_fma_f32 v[2:3], v[248:249], v[174:175], v[2:3] op_sel_hi:[1,0,1]
	v_pk_fma_f32 v[0:1], v[250:251], v[174:175], v[0:1] op_sel_hi:[1,0,1]
	ds_read_b128 v[236:239], v130 offset:45056
	ds_read_b128 v[240:243], v130 offset:46080
	ds_read_b128 v[244:247], v130 offset:47104
	ds_read_b128 v[248:251], v130 offset:48128
	s_waitcnt lgkmcnt(8)
	v_and_b32_e32 v180, 0xffff0000, v122
	v_and_b32_e32 v181, 0xffff0000, v124
	v_add_f32_e32 v174, v180, v181
	v_pk_fma_f32 v[80:81], v[204:205], v[174:175], v[80:81] op_sel_hi:[1,0,1]
	v_pk_fma_f32 v[74:75], v[206:207], v[174:175], v[74:75] op_sel_hi:[1,0,1]
	v_pk_fma_f32 v[72:73], v[208:209], v[174:175], v[72:73] op_sel_hi:[1,0,1]
	v_pk_fma_f32 v[70:71], v[210:211], v[174:175], v[70:71] op_sel_hi:[1,0,1]
	v_pk_fma_f32 v[68:69], v[212:213], v[174:175], v[68:69] op_sel_hi:[1,0,1]
	v_pk_fma_f32 v[66:67], v[214:215], v[174:175], v[66:67] op_sel_hi:[1,0,1]
	v_pk_fma_f32 v[2:3], v[216:217], v[174:175], v[2:3] op_sel_hi:[1,0,1]
	v_pk_fma_f32 v[0:1], v[218:219], v[174:175], v[0:1] op_sel_hi:[1,0,1]
	ds_read_b128 v[204:207], v130 offset:49152
	ds_read_b128 v[208:211], v130 offset:50176
	ds_read_b128 v[212:215], v130 offset:51200
	ds_read_b128 v[216:219], v130 offset:52224
	s_waitcnt lgkmcnt(8)
	v_lshlrev_b32_e32 v180, 16, v123
	v_lshlrev_b32_e32 v181, 16, v125
	v_add_f32_e32 v174, v180, v181
	v_pk_fma_f32 v[80:81], v[220:221], v[174:175], v[80:81] op_sel_hi:[1,0,1]
	v_pk_fma_f32 v[74:75], v[222:223], v[174:175], v[74:75] op_sel_hi:[1,0,1]
	v_pk_fma_f32 v[72:73], v[224:225], v[174:175], v[72:73] op_sel_hi:[1,0,1]
	v_pk_fma_f32 v[70:71], v[226:227], v[174:175], v[70:71] op_sel_hi:[1,0,1]
	v_pk_fma_f32 v[68:69], v[228:229], v[174:175], v[68:69] op_sel_hi:[1,0,1]
	v_pk_fma_f32 v[66:67], v[230:231], v[174:175], v[66:67] op_sel_hi:[1,0,1]
	v_pk_fma_f32 v[2:3], v[232:233], v[174:175], v[2:3] op_sel_hi:[1,0,1]
	v_pk_fma_f32 v[0:1], v[234:235], v[174:175], v[0:1] op_sel_hi:[1,0,1]
	ds_read_b128 v[220:223], v130 offset:53248
	ds_read_b128 v[224:227], v130 offset:54272
	ds_read_b128 v[228:231], v130 offset:55296
	ds_read_b128 v[232:235], v130 offset:56320
	s_waitcnt lgkmcnt(8)
	v_and_b32_e32 v180, 0xffff0000, v123
	v_and_b32_e32 v181, 0xffff0000, v125
	v_add_f32_e32 v174, v180, v181
	v_pk_fma_f32 v[80:81], v[236:237], v[174:175], v[80:81] op_sel_hi:[1,0,1]
	v_pk_fma_f32 v[74:75], v[238:239], v[174:175], v[74:75] op_sel_hi:[1,0,1]
	v_pk_fma_f32 v[72:73], v[240:241], v[174:175], v[72:73] op_sel_hi:[1,0,1]
	v_pk_fma_f32 v[70:71], v[242:243], v[174:175], v[70:71] op_sel_hi:[1,0,1]
	v_pk_fma_f32 v[68:69], v[244:245], v[174:175], v[68:69] op_sel_hi:[1,0,1]
	v_pk_fma_f32 v[66:67], v[246:247], v[174:175], v[66:67] op_sel_hi:[1,0,1]
	v_pk_fma_f32 v[2:3], v[248:249], v[174:175], v[2:3] op_sel_hi:[1,0,1]
	v_pk_fma_f32 v[0:1], v[250:251], v[174:175], v[0:1] op_sel_hi:[1,0,1]
	ds_read_b128 v[236:239], v130 offset:57344
	ds_read_b128 v[240:243], v130 offset:58368
	ds_read_b128 v[244:247], v130 offset:59392
	ds_read_b128 v[248:251], v130 offset:60416
	s_waitcnt lgkmcnt(8)
	s_waitcnt vmcnt(0)
	v_lshlrev_b32_e32 v180, 16, v126
	v_lshlrev_b32_e32 v181, 16, v128
	v_add_f32_e32 v174, v180, v181
	v_pk_fma_f32 v[80:81], v[204:205], v[174:175], v[80:81] op_sel_hi:[1,0,1]
	v_pk_fma_f32 v[74:75], v[206:207], v[174:175], v[74:75] op_sel_hi:[1,0,1]
	v_pk_fma_f32 v[72:73], v[208:209], v[174:175], v[72:73] op_sel_hi:[1,0,1]
	v_pk_fma_f32 v[70:71], v[210:211], v[174:175], v[70:71] op_sel_hi:[1,0,1]
	v_pk_fma_f32 v[68:69], v[212:213], v[174:175], v[68:69] op_sel_hi:[1,0,1]
	v_pk_fma_f32 v[66:67], v[214:215], v[174:175], v[66:67] op_sel_hi:[1,0,1]
	v_pk_fma_f32 v[2:3], v[216:217], v[174:175], v[2:3] op_sel_hi:[1,0,1]
	v_pk_fma_f32 v[0:1], v[218:219], v[174:175], v[0:1] op_sel_hi:[1,0,1]
	ds_read_b128 v[204:207], v130 offset:61440
	ds_read_b128 v[208:211], v130 offset:62464
	ds_read_b128 v[212:215], v130 offset:63488
	ds_read_b128 v[216:219], v130 offset:64512
	s_waitcnt lgkmcnt(8)
	v_and_b32_e32 v180, 0xffff0000, v126
	v_and_b32_e32 v181, 0xffff0000, v128
	v_add_f32_e32 v174, v180, v181
	v_pk_fma_f32 v[80:81], v[220:221], v[174:175], v[80:81] op_sel_hi:[1,0,1]
	v_pk_fma_f32 v[74:75], v[222:223], v[174:175], v[74:75] op_sel_hi:[1,0,1]
	v_pk_fma_f32 v[72:73], v[224:225], v[174:175], v[72:73] op_sel_hi:[1,0,1]
	v_pk_fma_f32 v[70:71], v[226:227], v[174:175], v[70:71] op_sel_hi:[1,0,1]
	v_pk_fma_f32 v[68:69], v[228:229], v[174:175], v[68:69] op_sel_hi:[1,0,1]
	v_pk_fma_f32 v[66:67], v[230:231], v[174:175], v[66:67] op_sel_hi:[1,0,1]
	v_pk_fma_f32 v[2:3], v[232:233], v[174:175], v[2:3] op_sel_hi:[1,0,1]
	v_pk_fma_f32 v[0:1], v[234:235], v[174:175], v[0:1] op_sel_hi:[1,0,1]
	s_waitcnt lgkmcnt(4)
	v_lshlrev_b32_e32 v180, 16, v127
	v_lshlrev_b32_e32 v181, 16, v129
	v_add_f32_e32 v174, v180, v181
	v_pk_fma_f32 v[80:81], v[236:237], v[174:175], v[80:81] op_sel_hi:[1,0,1]
	v_pk_fma_f32 v[74:75], v[238:239], v[174:175], v[74:75] op_sel_hi:[1,0,1]
	v_pk_fma_f32 v[72:73], v[240:241], v[174:175], v[72:73] op_sel_hi:[1,0,1]
	v_pk_fma_f32 v[70:71], v[242:243], v[174:175], v[70:71] op_sel_hi:[1,0,1]
	v_pk_fma_f32 v[68:69], v[244:245], v[174:175], v[68:69] op_sel_hi:[1,0,1]
	v_pk_fma_f32 v[66:67], v[246:247], v[174:175], v[66:67] op_sel_hi:[1,0,1]
	v_pk_fma_f32 v[2:3], v[248:249], v[174:175], v[2:3] op_sel_hi:[1,0,1]
	v_pk_fma_f32 v[0:1], v[250:251], v[174:175], v[0:1] op_sel_hi:[1,0,1]
	s_waitcnt lgkmcnt(0)
	v_and_b32_e32 v180, 0xffff0000, v127
	v_and_b32_e32 v181, 0xffff0000, v129
	v_add_f32_e32 v174, v180, v181
	v_pk_fma_f32 v[80:81], v[204:205], v[174:175], v[80:81] op_sel_hi:[1,0,1]
	v_pk_fma_f32 v[74:75], v[206:207], v[174:175], v[74:75] op_sel_hi:[1,0,1]
	v_pk_fma_f32 v[72:73], v[208:209], v[174:175], v[72:73] op_sel_hi:[1,0,1]
	v_pk_fma_f32 v[70:71], v[210:211], v[174:175], v[70:71] op_sel_hi:[1,0,1]
	v_pk_fma_f32 v[68:69], v[212:213], v[174:175], v[68:69] op_sel_hi:[1,0,1]
	v_pk_fma_f32 v[66:67], v[214:215], v[174:175], v[66:67] op_sel_hi:[1,0,1]
	v_pk_fma_f32 v[2:3], v[216:217], v[174:175], v[2:3] op_sel_hi:[1,0,1]
	v_pk_fma_f32 v[0:1], v[218:219], v[174:175], v[0:1] op_sel_hi:[1,0,1]
	s_mov_b64 s[8:9], exec
	v_and_b32_e32 v109, 60, v28
	global_load_dword v110, v109, s[18:19]
	ds_bpermute_b32 v92, v29, v80
	ds_bpermute_b32 v93, v29, v81
	ds_bpermute_b32 v94, v29, v74
	ds_bpermute_b32 v95, v29, v75
	ds_bpermute_b32 v96, v29, v72
	ds_bpermute_b32 v97, v29, v73
	ds_bpermute_b32 v98, v29, v70
	ds_bpermute_b32 v99, v29, v71
	s_waitcnt lgkmcnt(0)
	ds_bpermute_b32 v100, v29, v68
	ds_bpermute_b32 v101, v29, v69
	ds_bpermute_b32 v102, v29, v66
	ds_bpermute_b32 v103, v29, v67
	ds_bpermute_b32 v104, v29, v2
	ds_bpermute_b32 v105, v29, v3
	ds_bpermute_b32 v106, v29, v0
	ds_bpermute_b32 v107, v29, v1
	v_add_f32_e32 v80, v80, v92
	v_add_f32_e32 v81, v81, v93
	v_add_f32_e32 v74, v74, v94
	v_add_f32_e32 v75, v75, v95
	v_add_f32_e32 v72, v72, v96
	v_add_f32_e32 v73, v73, v97
	v_add_f32_e32 v70, v70, v98
	v_add_f32_e32 v71, v71, v99
	s_waitcnt lgkmcnt(0)
	ds_bpermute_b32 v92, v86, v80
	ds_bpermute_b32 v93, v86, v81
	ds_bpermute_b32 v94, v86, v74
	ds_bpermute_b32 v95, v86, v75
	ds_bpermute_b32 v96, v86, v72
	ds_bpermute_b32 v97, v86, v73
	ds_bpermute_b32 v98, v86, v70
	ds_bpermute_b32 v99, v86, v71
	v_add_f32_e32 v68, v68, v100
	v_add_f32_e32 v69, v69, v101
	v_add_f32_e32 v66, v66, v102
	v_add_f32_e32 v67, v67, v103
	v_add_f32_e32 v2, v2, v104
	v_add_f32_e32 v3, v3, v105
	v_add_f32_e32 v0, v0, v106
	v_add_f32_e32 v1, v1, v107
	s_waitcnt lgkmcnt(0)
	ds_bpermute_b32 v100, v86, v68
	ds_bpermute_b32 v101, v86, v69
	ds_bpermute_b32 v102, v86, v66
	ds_bpermute_b32 v103, v86, v67
	ds_bpermute_b32 v104, v86, v2
	ds_bpermute_b32 v105, v86, v3
	ds_bpermute_b32 v106, v86, v0
	ds_bpermute_b32 v107, v86, v1
	v_add_f32_e32 v80, v80, v92
	v_add_f32_e32 v81, v81, v93
	v_add_f32_e32 v74, v74, v94
	v_add_f32_e32 v75, v75, v95
	v_add_f32_e32 v72, v72, v96
	v_add_f32_e32 v73, v73, v97
	v_add_f32_e32 v70, v70, v98
	v_add_f32_e32 v71, v71, v99
	s_waitcnt lgkmcnt(0)
	ds_bpermute_b32 v92, v87, v80
	ds_bpermute_b32 v93, v87, v81
	ds_bpermute_b32 v94, v87, v74
	ds_bpermute_b32 v95, v87, v75
	ds_bpermute_b32 v96, v87, v72
	ds_bpermute_b32 v97, v87, v73
	ds_bpermute_b32 v98, v87, v70
	ds_bpermute_b32 v99, v87, v71
	v_add_f32_e32 v68, v68, v100
	v_add_f32_e32 v69, v69, v101
	v_add_f32_e32 v66, v66, v102
	v_add_f32_e32 v67, v67, v103
	v_add_f32_e32 v2, v2, v104
	v_add_f32_e32 v3, v3, v105
	v_add_f32_e32 v0, v0, v106
	v_add_f32_e32 v1, v1, v107
	s_waitcnt lgkmcnt(0)
	ds_bpermute_b32 v100, v87, v68
	ds_bpermute_b32 v101, v87, v69
	ds_bpermute_b32 v102, v87, v66
	ds_bpermute_b32 v103, v87, v67
	ds_bpermute_b32 v104, v87, v2
	ds_bpermute_b32 v105, v87, v3
	ds_bpermute_b32 v106, v87, v0
	ds_bpermute_b32 v107, v87, v1
	v_add_f32_e32 v80, v80, v92
	v_add_f32_e32 v81, v81, v93
	v_add_f32_e32 v74, v74, v94
	v_add_f32_e32 v75, v75, v95
	v_add_f32_e32 v72, v72, v96
	v_add_f32_e32 v73, v73, v97
	v_add_f32_e32 v70, v70, v98
	v_add_f32_e32 v71, v71, v99
	s_waitcnt lgkmcnt(0)
	ds_bpermute_b32 v92, v88, v80
	ds_bpermute_b32 v93, v88, v81
	ds_bpermute_b32 v94, v88, v74
	ds_bpermute_b32 v95, v88, v75
	ds_bpermute_b32 v96, v88, v72
	ds_bpermute_b32 v97, v88, v73
	ds_bpermute_b32 v98, v88, v70
	ds_bpermute_b32 v99, v88, v71
	v_add_f32_e32 v68, v68, v100
	v_add_f32_e32 v69, v69, v101
	v_add_f32_e32 v66, v66, v102
	v_add_f32_e32 v67, v67, v103
	v_add_f32_e32 v2, v2, v104
	v_add_f32_e32 v3, v3, v105
	v_add_f32_e32 v0, v0, v106
	v_add_f32_e32 v1, v1, v107
	s_waitcnt lgkmcnt(0)
	ds_bpermute_b32 v100, v88, v68
	ds_bpermute_b32 v101, v88, v69
	ds_bpermute_b32 v102, v88, v66
	ds_bpermute_b32 v103, v88, v67
	ds_bpermute_b32 v104, v88, v2
	ds_bpermute_b32 v105, v88, v3
	ds_bpermute_b32 v106, v88, v0
	ds_bpermute_b32 v107, v88, v1
	v_add_f32_e32 v80, v80, v92
	v_add_f32_e32 v81, v81, v93
	v_add_f32_e32 v74, v74, v94
	v_add_f32_e32 v75, v75, v95
	v_add_f32_e32 v72, v72, v96
	v_add_f32_e32 v73, v73, v97
	v_add_f32_e32 v70, v70, v98
	v_add_f32_e32 v71, v71, v99
	s_waitcnt lgkmcnt(0)
	ds_bpermute_b32 v92, v89, v80
	ds_bpermute_b32 v93, v89, v81
	ds_bpermute_b32 v94, v89, v74
	ds_bpermute_b32 v95, v89, v75
	ds_bpermute_b32 v96, v89, v72
	ds_bpermute_b32 v97, v89, v73
	ds_bpermute_b32 v98, v89, v70
	ds_bpermute_b32 v99, v89, v71
	v_add_f32_e32 v68, v68, v100
	v_add_f32_e32 v69, v69, v101
	v_add_f32_e32 v66, v66, v102
	v_add_f32_e32 v67, v67, v103
	v_add_f32_e32 v2, v2, v104
	v_add_f32_e32 v3, v3, v105
	v_add_f32_e32 v0, v0, v106
	v_add_f32_e32 v1, v1, v107
	s_waitcnt lgkmcnt(0)
	ds_bpermute_b32 v100, v89, v68
	ds_bpermute_b32 v101, v89, v69
	ds_bpermute_b32 v102, v89, v66
	ds_bpermute_b32 v103, v89, v67
	ds_bpermute_b32 v104, v89, v2
	ds_bpermute_b32 v105, v89, v3
	ds_bpermute_b32 v106, v89, v0
	ds_bpermute_b32 v107, v89, v1
	v_add_f32_e32 v80, v80, v92
	v_add_f32_e32 v81, v81, v93
	v_add_f32_e32 v74, v74, v94
	v_add_f32_e32 v75, v75, v95
	v_add_f32_e32 v72, v72, v96
	v_add_f32_e32 v73, v73, v97
	v_add_f32_e32 v70, v70, v98
	v_add_f32_e32 v71, v71, v99
	s_waitcnt lgkmcnt(0)
	ds_bpermute_b32 v92, v90, v80
	ds_bpermute_b32 v93, v90, v81
	ds_bpermute_b32 v94, v90, v74
	ds_bpermute_b32 v95, v90, v75
	ds_bpermute_b32 v96, v90, v72
	ds_bpermute_b32 v97, v90, v73
	ds_bpermute_b32 v98, v90, v70
	ds_bpermute_b32 v99, v90, v71
	v_add_f32_e32 v68, v68, v100
	v_add_f32_e32 v69, v69, v101
	v_add_f32_e32 v66, v66, v102
	v_add_f32_e32 v67, v67, v103
	v_add_f32_e32 v2, v2, v104
	v_add_f32_e32 v3, v3, v105
	v_add_f32_e32 v0, v0, v106
	v_add_f32_e32 v1, v1, v107
	s_waitcnt lgkmcnt(0)
	ds_bpermute_b32 v100, v90, v68
	ds_bpermute_b32 v101, v90, v69
	ds_bpermute_b32 v102, v90, v66
	ds_bpermute_b32 v103, v90, v67
	ds_bpermute_b32 v104, v90, v2
	ds_bpermute_b32 v105, v90, v3
	ds_bpermute_b32 v106, v90, v0
	ds_bpermute_b32 v107, v90, v1
	v_add_f32_e32 v80, v80, v92
	v_add_f32_e32 v81, v81, v93
	v_add_f32_e32 v74, v74, v94
	v_add_f32_e32 v75, v75, v95
	v_add_f32_e32 v72, v72, v96
	v_add_f32_e32 v73, v73, v97
	v_add_f32_e32 v70, v70, v98
	v_add_f32_e32 v71, v71, v99
	s_waitcnt lgkmcnt(0)
	v_add_f32_e32 v68, v68, v100
	v_add_f32_e32 v69, v69, v101
	v_add_f32_e32 v66, v66, v102
	v_add_f32_e32 v67, v67, v103
	v_add_f32_e32 v2, v2, v104
	v_add_f32_e32 v3, v3, v105
	v_add_f32_e32 v0, v0, v106
	v_add_f32_e32 v1, v1, v107
	v_mov_b32_e32 v108, v80
	s_mov_b64 vcc, 2
	s_mov_b64 s[10:11], 4
	v_cndmask_b32_e32 v108, v108, v81, vcc
	s_mov_b64 vcc, 8
	v_cndmask_b32_e64 v108, v108, v74, s[10:11]
	s_mov_b64 s[10:11], 16
	v_cndmask_b32_e32 v108, v108, v75, vcc
	s_mov_b64 vcc, 32
	v_cndmask_b32_e64 v108, v108, v72, s[10:11]
	s_mov_b64 s[10:11], 64
	v_cndmask_b32_e32 v108, v108, v73, vcc
	s_mov_b64 vcc, 128
	v_cndmask_b32_e64 v108, v108, v70, s[10:11]
	s_mov_b64 s[10:11], 256
	v_cndmask_b32_e32 v108, v108, v71, vcc
	s_mov_b64 vcc, 512
	v_cndmask_b32_e64 v108, v108, v68, s[10:11]
	s_mov_b64 s[10:11], 1024
	v_cndmask_b32_e32 v108, v108, v69, vcc
	s_mov_b64 vcc, 2048
	v_cndmask_b32_e64 v108, v108, v66, s[10:11]
	s_mov_b64 s[10:11], 4096
	v_cndmask_b32_e32 v108, v108, v67, vcc
	s_mov_b64 vcc, 8192
	v_cndmask_b32_e64 v108, v108, v2, s[10:11]
	s_mov_b64 s[10:11], 16384
	v_cndmask_b32_e32 v108, v108, v3, vcc
	s_mov_b64 vcc, 32768
	v_cndmask_b32_e64 v108, v108, v0, s[10:11]
	v_cndmask_b32_e32 v108, v108, v1, vcc
	s_waitcnt vmcnt(0)
	v_add_f32_e32 v108, v110, v108
	v_mul_f32_e64 v111, |v108|, s97
	v_exp_f32_e32 v111, v111
	s_nop 0
	v_add_f32_e32 v112, 1.0, v111
	v_log_f32_e32 v112, v112
	v_fmamk_f32 v113, v111, 0xbe800000, v194
	v_fma_f32 v113, -v111, v113, 0.5
	v_fma_f32 v113, -v111, v113, 1.0
	v_mul_f32_e32 v113, v111, v113
	v_mul_f32_e32 v61, 0x3f317217, v112
	v_fma_f32 v61, v112, s76, -v61
	v_fmac_f32_e32 v61, 0x3377d1cf, v112
	v_fmac_f32_e32 v61, 0x3f317217, v112
	v_cmp_ngt_f32_e32 vcc, s90, v111
	v_ashrrev_i32_e32 v79, 31, v78
	v_lshl_add_u64 v[62:63], v[78:79], 2, s[34:35]
	v_cndmask_b32_e32 v61, v113, v61, vcc
	v_mul_hi_i32_i24_e32 v65, 0x20400, v76
	v_mul_i32_i24_e32 v64, 0x20400, v76
	v_max_f32_e32 v108, v108, v108
	v_min_f32_e32 v108, 0, v108
	v_lshl_add_u64 v[62:63], v[62:63], 0, v[64:65]
	v_mul_u32_u24_e32 v64, 0x810, v109
	v_mov_b32_e32 v65, 0
	v_sub_f32_e32 v108, v108, v61
	v_lshl_add_u64 v[62:63], v[62:63], 0, v[64:65]
	s_mov_b64 exec, 0xffff
	global_store_dword v[62:63], v108, off
	s_mov_b64 exec, s[8:9]
	s_branch .LBB0_1110
